# c24 + ALiBi operand trim (c36) + all K-fragment reads issued up front (c22) + DIFF rescale threshold 80 (c30), combined
# speedup vs baseline: 1.0168x; 1.0003x over previous
.LBB0_1422:
	s_barrier
	s_lshl_b32 s18, s44, 14
	s_add_i32 s52, s81, s18
	s_mov_b32 m0, s52
	v_lshl_add_u64 v[0:1], v[194:195], 0, s[14:15]
	global_load_lds_dwordx4 v[194:195], off
	s_add_i32 m0, s52, 0x2000
	s_mul_i32 s52, s54, 0x2100
	s_add_i32 s52, s22, s52
	global_load_lds_dwordx4 v[0:1], off
	s_add_i32 m0, s52, 0xc000
	s_add_i32 s52, s45, -1
	s_cmp_lt_u32 s52, s2
	s_cselect_b32 s55, s52, s3
	s_lshl_b32 s56, s55, 6
	v_mad_u64_u32 v[0:1], s[52:53], s56, v209, v[192:193]
	v_lshl_add_u64 v[0:1], v[0:1], 0, s[10:11]
	global_load_lds_dwordx4 v[0:1], off
	s_mul_i32 s52, s55, 0x60000
	s_mul_hi_u32 s53, s56, 0x1800
	s_mul_i32 s55, s69, 0x2100
	s_add_i32 s71, s55, 0
	s_sub_i32 s55, s65, 64
	v_cvt_f32_u32_e32 v0, s55
	v_add_u32_e32 v166, s71, v220
	v_add_u32_e32 v167, s71, v217
	ds_read_b128 v[4:7], v166 offset:49152
	ds_read_b128 v[8:11], v167 offset:49152
	ds_read_b128 v[170:173], v166 offset:51264
	ds_read_b128 v[174:177], v167 offset:51264
	ds_read_b128 v[178:181], v166 offset:53376
	ds_read_b128 v[182:185], v167 offset:53376
	ds_read_b128 v[198:201], v166 offset:55488
	ds_read_b128 v[230:233], v167 offset:55488
	v_sub_f32_e32 v196, v0, v161
	v_fma_f32 v0, v210, v196, -v221
	v_and_b32_e32 v1, 0xffff0000, v0
	v_sub_f32_e32 v0, v0, v1
	v_and_b32_e32 v2, 0xffff0000, v0
	v_sub_f32_e32 v0, v0, v2
	v_perm_b32 v1, v2, v1, s99
	v_lshrrev_b32_e32 v2, 16, v0
	v_mov_b32_e32 v0, v160
	s_nop 1
	v_mfma_f32_32x32x16_bf16 v[128:143], v[248:251], v[0:3], 0
	v_add_f32_e32 v226, v96, v97
	v_add_f32_e32 v226, v98, v226
	v_add_f32_e32 v226, v99, v226
	v_add_f32_e32 v226, v100, v226
	v_mfma_f32_32x32x16_bf16 v[112:127], v[252:255], v[0:3], 0
	v_add_f32_e32 v1, v101, v226
	v_add_f32_e32 v1, v102, v1
	s_waitcnt lgkmcnt(6)
	v_mfma_f32_32x32x16_bf16 v[128:143], v[8:11], v[156:159], v[128:143]
	v_add_f32_e32 v1, v103, v1
	v_add_f32_e32 v1, v104, v1
	v_add_f32_e32 v1, v105, v1
	v_add_f32_e32 v1, v106, v1
	v_add_f32_e32 v1, v107, v1
	v_add_f32_e32 v1, v108, v1
	v_add_f32_e32 v1, v109, v1
	v_mfma_f32_32x32x16_bf16 v[112:127], v[4:7], v[156:159], v[112:127]
	v_add_f32_e32 v1, v110, v1
	v_add_f32_e32 v1, v111, v1
	v_add_f32_e32 v1, v80, v1
	v_add_f32_e32 v1, v81, v1
	v_add_f32_e32 v1, v82, v1
	v_add_f32_e32 v1, v83, v1
	s_waitcnt lgkmcnt(4)
	v_mfma_f32_32x32x16_bf16 v[128:143], v[174:177], v[152:155], v[128:143]
	v_add_f32_e32 v1, v84, v1
	v_add_f32_e32 v1, v85, v1
	v_add_f32_e32 v1, v86, v1
	v_add_f32_e32 v1, v87, v1
	v_add_f32_e32 v1, v88, v1
	v_add_f32_e32 v1, v89, v1
	v_add_f32_e32 v1, v90, v1
	v_mfma_f32_32x32x16_bf16 v[112:127], v[170:173], v[152:155], v[112:127]
	v_add_f32_e32 v1, v91, v1
	v_add_f32_e32 v1, v92, v1
	v_add_f32_e32 v1, v93, v1
	v_add_f32_e32 v1, v94, v1
	v_add_f32_e32 v223, v95, v1
	v_mov_b32_e32 v224, v223
	s_waitcnt lgkmcnt(2)
	v_mfma_f32_32x32x16_bf16 v[128:143], v[182:185], v[148:151], v[128:143]
	v_permlane32_swap_b32_e32 v223, v224
	v_mfma_f32_32x32x16_bf16 v[112:127], v[178:181], v[148:151], v[112:127]
	v_cvt_pk_bf16_f32 v166, v96, v97
	v_cvt_pk_bf16_f32 v167, v98, v99
	v_cvt_pk_bf16_f32 v168, v100, v101
	v_cvt_pk_bf16_f32 v169, v102, v103
	v_cvt_pk_bf16_f32 v12, v104, v105
	v_cvt_pk_bf16_f32 v13, v106, v107
	s_waitcnt lgkmcnt(0)
	v_mfma_f32_32x32x16_bf16 v[128:143], v[230:233], v[144:147], v[128:143]
	v_cvt_pk_bf16_f32 v14, v108, v109
	v_cvt_pk_bf16_f32 v15, v110, v111
	v_cvt_pk_bf16_f32 v8, v80, v81
	v_cvt_pk_bf16_f32 v9, v82, v83
	v_cvt_pk_bf16_f32 v10, v84, v85
	v_cvt_pk_bf16_f32 v11, v86, v87
	v_mfma_f32_32x32x16_bf16 v[112:127], v[198:201], v[144:147], v[112:127]
	v_cvt_pk_bf16_f32 v4, v88, v89
	v_cvt_pk_bf16_f32 v5, v90, v91
	v_cvt_pk_bf16_f32 v6, v92, v93
	v_cvt_pk_bf16_f32 v7, v94, v95
	v_lshl_add_u32 v1, s54, 14, v215
	ds_read_b64_tr_b16 v[182:183], v1 offset:0
	ds_read_b64_tr_b16 v[184:185], v1 offset:0x800
	ds_read_b64_tr_b16 v[178:179], v1 offset:0x1000
	ds_read_b64_tr_b16 v[180:181], v1 offset:0x1800
	s_add_i32 s70, s45, -3
	s_add_i32 s54, s19, s45
	ds_read_b64_tr_b16 v[174:175], v1 offset:0x2000
	s_cmp_eq_u32 s54, 3
	ds_read_b64_tr_b16 v[176:177], v1 offset:0x2800
	s_cselect_b64 s[54:55], -1, 0
	ds_read_b64_tr_b16 v[170:171], v1 offset:0x3000
	v_cndmask_b32_e64 v2, 0, 1, s[54:55]
	ds_read_b64_tr_b16 v[172:173], v1 offset:0x3800
	s_cmp_lt_i32 s70, s31
	s_cbranch_scc0 .Lold_odd
	v_max3_f32 v245, v128, v129, v130
	v_max3_f32 v246, v112, v113, v114
	v_max3_f32 v245, v245, v131, v132
	v_max3_f32 v246, v246, v115, v116
	v_max3_f32 v245, v245, v133, v134
	v_max3_f32 v246, v246, v117, v118
	v_max3_f32 v245, v245, v135, v136
	v_max3_f32 v246, v246, v119, v120
	v_max3_f32 v245, v245, v137, v138
	v_max3_f32 v246, v246, v121, v122
	v_max3_f32 v245, v245, v139, v140
	v_max3_f32 v246, v246, v123, v124
	v_max3_f32 v245, v245, v141, v142
	v_max3_f32 v246, v246, v125, v126
	v_max_f32_e32 v245, v245, v143
	v_max_f32_e32 v246, v246, v127
	v_max_f32_e32 v245, v245, v246
	v_mov_b32_e32 v246, v245
	s_nop 1
	v_permlane32_swap_b32_e32 v245, v246
	v_max_f32_e32 v245, v245, v246
	v_cmp_ge_f32_e32 vcc, s68, v245
	s_cmp_eq_u64 vcc, exec
	v_mov_b32_e32 v225, 1.0
	s_cbranch_scc0 .Lf_odd_resc

.LBB0_1437:
	s_waitcnt vmcnt(0)
	s_add_i32 s54, s44, 1
	s_cmp_lg_u32 s44, 2
	s_cselect_b32 s67, s54, 0
	s_waitcnt vmcnt(0)
	s_barrier
	s_lshl_b32 s66, s67, 14
	s_add_i32 s54, s81, s66
	v_lshl_add_u64 v[4:5], v[190:191], 0, s[52:53]
	s_mov_b32 m0, s54
	s_add_i32 s52, s71, s82
	global_load_lds_dwordx4 v[4:5], off
	v_lshl_add_u64 v[4:5], v[4:5], 0, s[14:15]
	s_add_i32 m0, s54, 0x2000
	s_add_i32 s52, s52, s27
	global_load_lds_dwordx4 v[4:5], off
	s_add_i32 m0, s52, 0xc000
	s_cmp_ge_u32 s45, s2
	s_cselect_b64 s[52:53], -1, 0
	s_cmp_lt_u32 s45, s2
	s_cselect_b32 s54, s45, s3
	s_lshl_b32 s54, s54, 6
	v_mad_u64_u32 v[4:5], s[54:55], s54, v209, v[192:193]
	v_lshl_add_u64 v[4:5], v[4:5], 0, s[10:11]
	global_load_lds_dwordx4 v[4:5], off
	v_cvt_f32_u32_e32 v1, s65
	s_mul_i32 s54, s44, 0x2100
	s_add_i32 s54, s54, 0
	v_add_u32_e32 v166, s54, v220
	v_sub_f32_e32 v196, v1, v161
	v_add_u32_e32 v167, s54, v217
	v_fma_f32 v1, v210, v196, -v221
	ds_read_b128 v[4:7], v166 offset:49152
	ds_read_b128 v[8:11], v167 offset:49152
	ds_read_b128 v[170:173], v166 offset:51264
	ds_read_b128 v[174:177], v167 offset:51264
	ds_read_b128 v[178:181], v166 offset:53376
	ds_read_b128 v[182:185], v167 offset:53376
	ds_read_b128 v[198:201], v166 offset:55488
	ds_read_b128 v[230:233], v167 offset:55488
	v_and_b32_e32 v2, 0xffff0000, v1
	v_sub_f32_e32 v1, v1, v2
	v_and_b32_e32 v12, 0xffff0000, v1
	v_sub_f32_e32 v1, v1, v12
	v_perm_b32 v12, v12, v2, s99
	v_lshrrev_b32_e32 v2, 16, v1
	v_mov_b32_e32 v1, v12
	s_nop 1
	v_mfma_f32_32x32x16_bf16 v[128:143], v[248:251], v[0:3], 0
	v_add_f32_e32 v226, v96, v97
	v_add_f32_e32 v226, v98, v226
	v_add_f32_e32 v226, v99, v226
	v_add_f32_e32 v226, v100, v226
	s_nop 0
	v_mfma_f32_32x32x16_bf16 v[112:127], v[252:255], v[0:3], 0
	v_add_f32_e32 v1, v101, v226
	v_add_f32_e32 v1, v102, v1
	s_waitcnt lgkmcnt(6)
	v_mfma_f32_32x32x16_bf16 v[128:143], v[8:11], v[156:159], v[128:143]
	v_add_f32_e32 v1, v103, v1
	v_add_f32_e32 v1, v104, v1
	v_add_f32_e32 v1, v105, v1
	v_add_f32_e32 v1, v106, v1
	v_add_f32_e32 v1, v107, v1
	v_add_f32_e32 v1, v108, v1
	v_add_f32_e32 v1, v109, v1
	v_mfma_f32_32x32x16_bf16 v[112:127], v[4:7], v[156:159], v[112:127]
	v_add_f32_e32 v1, v110, v1
	v_add_f32_e32 v1, v111, v1
	v_add_f32_e32 v1, v80, v1
	v_add_f32_e32 v1, v81, v1
	v_add_f32_e32 v1, v82, v1
	v_add_f32_e32 v1, v83, v1
	s_waitcnt lgkmcnt(4)
	v_mfma_f32_32x32x16_bf16 v[128:143], v[174:177], v[152:155], v[128:143]
	v_add_f32_e32 v1, v84, v1
	v_add_f32_e32 v1, v85, v1
	v_add_f32_e32 v1, v86, v1
	v_add_f32_e32 v1, v87, v1
	v_add_f32_e32 v1, v88, v1
	v_add_f32_e32 v1, v89, v1
	v_add_f32_e32 v1, v90, v1
	v_mfma_f32_32x32x16_bf16 v[112:127], v[170:173], v[152:155], v[112:127]
	v_add_f32_e32 v1, v91, v1
	v_add_f32_e32 v1, v92, v1
	v_add_f32_e32 v1, v93, v1
	v_add_f32_e32 v1, v94, v1
	v_add_f32_e32 v1, v95, v1
	v_mov_b32_e32 v2, v1
	s_waitcnt lgkmcnt(2)
	v_mfma_f32_32x32x16_bf16 v[128:143], v[182:185], v[148:151], v[128:143]
	v_permlane32_swap_b32_e32 v1, v2
	v_mfma_f32_32x32x16_bf16 v[112:127], v[178:181], v[148:151], v[112:127]
	v_cvt_pk_bf16_f32 v166, v96, v97
	v_cvt_pk_bf16_f32 v167, v98, v99
	v_cvt_pk_bf16_f32 v168, v100, v101
	v_cvt_pk_bf16_f32 v169, v102, v103
	v_cvt_pk_bf16_f32 v12, v104, v105
	v_cvt_pk_bf16_f32 v13, v106, v107
	s_waitcnt lgkmcnt(0)
	v_mfma_f32_32x32x16_bf16 v[128:143], v[230:233], v[144:147], v[128:143]
	v_cvt_pk_bf16_f32 v14, v108, v109
	v_cvt_pk_bf16_f32 v15, v110, v111
	v_cvt_pk_bf16_f32 v8, v80, v81
	v_cvt_pk_bf16_f32 v9, v82, v83
	v_cvt_pk_bf16_f32 v10, v84, v85
	v_cvt_pk_bf16_f32 v11, v86, v87
	v_mfma_f32_32x32x16_bf16 v[112:127], v[198:201], v[144:147], v[112:127]
	v_cvt_pk_bf16_f32 v4, v88, v89
	v_cvt_pk_bf16_f32 v5, v90, v91
	v_cvt_pk_bf16_f32 v6, v92, v93
	v_cvt_pk_bf16_f32 v7, v94, v95
	v_lshl_add_u32 v162, s69, 14, v215
	ds_read_b64_tr_b16 v[182:183], v162 offset:0
	ds_read_b64_tr_b16 v[184:185], v162 offset:0x800
	ds_read_b64_tr_b16 v[178:179], v162 offset:0x1000
	ds_read_b64_tr_b16 v[180:181], v162 offset:0x1800
	s_add_i32 s54, s64, s45
	ds_read_b64_tr_b16 v[174:175], v162 offset:0x2000
	s_cmp_eq_u32 s54, 4
	ds_read_b64_tr_b16 v[176:177], v162 offset:0x2800
	s_cselect_b64 s[54:55], -1, 0
	ds_read_b64_tr_b16 v[170:171], v162 offset:0x3000
	v_cndmask_b32_e64 v80, 0, 1, s[54:55]
	ds_read_b64_tr_b16 v[172:173], v162 offset:0x3800
	s_add_i32 s98, s70, 2
	s_cmp_le_i32 s98, s31
	s_cbranch_scc0 .Lold_even
	v_max3_f32 v245, v128, v129, v130
	v_max3_f32 v246, v112, v113, v114
	v_max3_f32 v245, v245, v131, v132
	v_max3_f32 v246, v246, v115, v116
	v_max3_f32 v245, v245, v133, v134
	v_max3_f32 v246, v246, v117, v118
	v_max3_f32 v245, v245, v135, v136
	v_max3_f32 v246, v246, v119, v120
	v_max3_f32 v245, v245, v137, v138
	v_max3_f32 v246, v246, v121, v122
	v_max3_f32 v245, v245, v139, v140
	v_max3_f32 v246, v246, v123, v124
	v_max3_f32 v245, v245, v141, v142
	v_max3_f32 v246, v246, v125, v126
	v_max_f32_e32 v245, v245, v143
	v_max_f32_e32 v246, v246, v127
	v_max_f32_e32 v245, v245, v246
	v_mov_b32_e32 v246, v245
	s_nop 1
	v_permlane32_swap_b32_e32 v245, v246
	v_max_f32_e32 v245, v245, v246
	v_cmp_ge_f32_e32 vcc, s68, v245
	s_cmp_eq_u64 vcc, exec
	v_mov_b32_e32 v196, 1.0
	s_cbranch_scc0 .Lf_even_resc
